# work-queue prefetch atomic left in flight during the item (waited at item end) on top of coop indexer + select
# speedup vs baseline: 1.0318x; 1.0049x over previous
.LBB0_531:
	v_mov_b32_e32 v205, 0
	s_mov_b64 s[0:1], exec
	v_readlane_b32 s2, v250, 16
	v_readlane_b32 s3, v250, 17
	s_and_b64 s[2:3], s[0:1], s[2:3]
	s_mov_b64 exec, s[2:3]
	s_cbranch_execz .LBB0_535
	v_readlane_b32 s4, v250, 14
	v_readlane_b32 s5, v250, 15
	v_mov_b32_e32 v205, 1
	s_nop 4
	global_atomic_add v205, v1, v205, s[4:5] sc0

.LBB0_1975:
	s_waitcnt lgkmcnt(0)
	s_barrier
	s_mov_b64 s[0:1], exec
	v_readlane_b32 s2, v250, 16
	v_readlane_b32 s3, v250, 17
	s_and_b64 s[2:3], s[0:1], s[2:3]
	s_mov_b64 exec, s[2:3]
	s_cbranch_execz .LBB0_530
	s_waitcnt vmcnt(0)
	ds_write_b32 v200, v205
	s_branch .LBB0_530
